# v30 with the decode loop pacing lowered from s_sleep 32 to s_sleep 20 (decode items are shorter since the item-start rework)
# speedup vs baseline: 1.0075x; 1.0023x over previous
; #define MFMA16(a, b, c) __builtin_amdgcn_mfma_f32_16x16x32_bf16((a), (b), (c), 0, 0, 0)
; __device__ __forceinline__ bf16x8 cvt8(f32x4 a, f32x4 b) { v4u w = {pk2(a[0], a[1]), pk2(a[2], a[3]), pk2(b[0], b[1]), pk2(b[2], b[3])}; return __builtin_bit_cast(bf16x8, w); }
; #define DEC_LOADV(VB_, NEW_) do { _Pragma("unroll") for (int j = 0; j < 8; ++j) { int key_ = (j < 4) ? vkey0 + j : 16 + vkey0 + (j - 4); if (NEW_) key_ = key_ > 3 ? 3 : key_; \
;         _Pragma("unroll") for (int hf = 0; hf < 2; ++hf) vr[j][hf] = *(const f32x4*)((VB_) + (size_t)key_ * 512 + 64 * hf + 4 * n); } } while (0)
; __device__ __forceinline__ void decode_unit(int item, const float* ck, const float* cv, const int* pt, const bf16* QB, const float* ksamp, const float* vsamp, bf16* MIX_unused_, LAS unsigned char* lds, const LAS float* BL, float lam, float* PART, gu32* dcnt, bf16* MIX, gu32* rdy4) {
;     ...
;     const int ptv = pt[b * NPAGES + (lane & 15)];
;     const float* kbase; const float* vbase; int key0; bool isnew;
;     DEC_BASES(0, kbase, vbase, key0, isnew);
;     DEC_LOADK(kbase, isnew);
;     for (int i = 0; i < NIT; ++i) {
;         __builtin_amdgcn_sched_barrier(0);
;         DEC_LOADV(vbase, isnew);
;         __builtin_amdgcn_sched_barrier(0);
;         f32x4 s[2];
; #pragma unroll
;         for (int sub = 0; sub < 2; ++sub) {
;             s[sub] = (f32x4){0.f, 0.f, 0.f, 0.f};
; #pragma unroll
;             for (int mp = 0; mp < 2; ++mp)
; #pragma unroll
;                 for (int ks = 0; ks < 2; ++ks) s[sub] = MFMA16(cvt8(kr[sub][mp][ks][0], kr[sub][mp][ks][1]), qfl[(mp * 2 + ks) * 64], s[sub]);
;         }
;         const int key0c = key0; const bool isnewc = isnew;
;         __builtin_amdgcn_sched_barrier(0);
;         const float* vb_cur = vbase;
;         if (i + 1 < NIT) { DEC_BASES(i + 1, kbase, vbase, key0, isnew); DEC_LOADK(kbase, isnew); }
.LBB0_665:
	s_sleep 20
	v_lshlrev_b32_e32 v98, 2, v194
	v_lshlrev_b32_e32 v98, 2, v98
	v_cndmask_b32_e64 v100, v223, v225, s[76:77]
	v_cndmask_b32_e64 v104, v226, v227, s[76:77]
	v_cndmask_b32_e64 v108, v228, v229, s[76:77]
	v_lshl_add_u64 v[132:133], s[78:79], 0, v[98:99]
	v_lshlrev_b32_e32 v100, 11, v100
	v_mov_b32_e32 v101, v99
	v_lshlrev_b32_e32 v104, 11, v104
	v_mov_b32_e32 v105, v99
	v_lshlrev_b32_e32 v108, 11, v108
	v_mov_b32_e32 v109, v99
	v_cndmask_b32_e64 v112, v198, v246, s[76:77]
	v_mov_b32_e32 v113, v99
	v_cndmask_b32_e64 v116, v200, v246, s[76:77]
	v_mov_b32_e32 v117, v99
	v_cndmask_b32_e64 v120, v202, v246, s[76:77]
	v_mov_b32_e32 v121, v99
	v_cndmask_b32_e64 v128, v204, v246, s[76:77]
	v_mov_b32_e32 v129, v99
	v_cndmask_b32_e64 v134, v206, v246, s[76:77]
	v_mov_b32_e32 v135, v99
	v_lshl_add_u64 v[100:101], v[132:133], 0, v[100:101]
	v_lshl_add_u64 v[104:105], v[132:133], 0, v[104:105]
	v_lshl_add_u64 v[108:109], v[132:133], 0, v[108:109]
	v_lshl_add_u64 v[112:113], v[132:133], 0, v[112:113]
	v_lshl_add_u64 v[116:117], v[132:133], 0, v[116:117]
	v_lshl_add_u64 v[120:121], v[132:133], 0, v[120:121]
	v_lshl_add_u64 v[128:129], v[132:133], 0, v[128:129]
	v_lshl_add_u64 v[132:133], v[132:133], 0, v[134:135]
	global_load_dwordx4 v[124:127], v[100:101], off
	s_nop 0
	global_load_dwordx4 v[100:103], v[100:101], off offset:256
	s_nop 0
	global_load_dwordx4 v[136:139], v[104:105], off
	s_nop 0
	global_load_dwordx4 v[104:107], v[104:105], off offset:256
	s_nop 0
	global_load_dwordx4 v[140:143], v[108:109], off
	s_nop 0
	global_load_dwordx4 v[108:111], v[108:109], off offset:256
	s_nop 0
	global_load_dwordx4 v[144:147], v[112:113], off
	s_nop 0
	global_load_dwordx4 v[112:115], v[112:113], off offset:256
	s_nop 0
	global_load_dwordx4 v[148:151], v[116:117], off
	s_nop 0
	global_load_dwordx4 v[116:119], v[116:117], off offset:256
	s_nop 0
	global_load_dwordx4 v[152:155], v[120:121], off
	s_nop 0
	global_load_dwordx4 v[120:123], v[120:121], off offset:256
	s_nop 0
	global_load_dwordx4 v[156:159], v[128:129], off
	s_nop 0
	global_load_dwordx4 v[128:131], v[128:129], off offset:256
	s_nop 0
	global_load_dwordx4 v[160:163], v[132:133], off
	s_nop 0
	global_load_dwordx4 v[132:135], v[132:133], off offset:256
	s_waitcnt vmcnt(30)
	v_cvt_pk_bf16_f32 v62, v62, v63
	v_cvt_pk_bf16_f32 v63, v64, v65
	v_cvt_pk_bf16_f32 v64, v58, v59
	v_cvt_pk_bf16_f32 v65, v60, v61
	ds_read_b128 v[58:61], v213 offset:40960
	s_waitcnt vmcnt(28)
	v_cvt_pk_bf16_f32 v54, v54, v55
	v_cvt_pk_bf16_f32 v55, v56, v57
	v_cvt_pk_bf16_f32 v56, v50, v51
	v_cvt_pk_bf16_f32 v57, v52, v53
	ds_read_b128 v[50:53], v213 offset:41984
	s_waitcnt lgkmcnt(1)
	v_mfma_f32_16x16x32_bf16 v[62:65], v[62:65], v[58:61], 0
	s_waitcnt vmcnt(26)
	v_cvt_pk_bf16_f32 v46, v46, v47
	v_cvt_pk_bf16_f32 v47, v48, v49
	v_cvt_pk_bf16_f32 v48, v42, v43
	v_cvt_pk_bf16_f32 v49, v44, v45
	ds_read_b128 v[42:45], v213 offset:43008
	s_waitcnt lgkmcnt(1)
	v_mfma_f32_16x16x32_bf16 v[54:57], v[54:57], v[50:53], v[62:65]
	s_waitcnt vmcnt(24)
	v_cvt_pk_bf16_f32 v38, v38, v39
	v_cvt_pk_bf16_f32 v39, v40, v41
	v_cvt_pk_bf16_f32 v40, v34, v35
	v_cvt_pk_bf16_f32 v41, v36, v37
	ds_read_b128 v[34:37], v213 offset:44032
	s_waitcnt lgkmcnt(1)
	v_mfma_f32_16x16x32_bf16 v[46:49], v[46:49], v[42:45], v[54:57]
	s_waitcnt lgkmcnt(0)
	v_mfma_f32_16x16x32_bf16 v[164:167], v[38:41], v[34:37], v[46:49]
	s_waitcnt vmcnt(22)
	v_cvt_pk_bf16_f32 v38, v94, v95
	v_cvt_pk_bf16_f32 v39, v96, v97
	s_waitcnt vmcnt(22)
	v_cvt_pk_bf16_f32 v40, v86, v87
	v_cvt_pk_bf16_f32 v41, v88, v89
	s_waitcnt vmcnt(20)
	v_cvt_pk_bf16_f32 v46, v90, v91
	v_cvt_pk_bf16_f32 v47, v92, v93
	s_waitcnt vmcnt(19)
	v_cvt_pk_bf16_f32 v48, v82, v83
	v_cvt_pk_bf16_f32 v49, v84, v85
	v_mfma_f32_16x16x32_bf16 v[38:41], v[38:41], v[58:61], 0
	s_nop 0
	v_mfma_f32_16x16x32_bf16 v[38:41], v[46:49], v[50:53], v[38:41]
	s_waitcnt vmcnt(18)
	v_cvt_pk_bf16_f32 v46, v70, v71
	v_cvt_pk_bf16_f32 v47, v72, v73
	s_waitcnt vmcnt(17)
	v_cvt_pk_bf16_f32 v48, v78, v79
	v_cvt_pk_bf16_f32 v49, v80, v81
	s_nop 1
	v_mfma_f32_16x16x32_bf16 v[38:41], v[46:49], v[42:45], v[38:41]
	s_waitcnt vmcnt(16)
	v_cvt_pk_bf16_f32 v42, v66, v67
	v_cvt_pk_bf16_f32 v43, v68, v69
	s_waitcnt vmcnt(16)
	v_cvt_pk_bf16_f32 v44, v74, v75
	v_cvt_pk_bf16_f32 v45, v76, v77
	s_nop 1
	v_mfma_f32_16x16x32_bf16 v[168:171], v[42:45], v[34:37], v[38:41]
	s_cmpk_eq_i32 s91, 0x1c0
	s_cselect_b64 s[74:75], -1, 0
	s_and_b64 vcc, exec, s[74:75]
	s_cbranch_vccnz .LBB0_667
	s_lshr_b32 s78, s94, 2
	v_readlane_b32 s78, v217, s78
	s_ashr_i32 s79, s78, 31
	s_and_b32 s80, s95, 0xc000
	s_lshl_b64 s[78:79], s[78:79], 16
	s_or_b32 s78, s78, s80
	s_or_b64 s[78:79], s[78:79], s[28:29]
	s_lshl_b64 s[78:79], s[78:79], 2
	s_add_u32 s80, s20, s78
	s_addc_u32 s81, s21, s79
	s_add_u32 s78, s22, s78
	s_addc_u32 s79, s23, s79
	s_add_i32 s96, s93, s91
	v_mov_b32_e32 v34, v232
	v_mov_b64_e32 v[66:67], v[208:209]
	s_branch .LBB0_668
